# A-units: L2 touch-prefetch of the next A-unit's K/V/Q lines during compute (3 dword loads per thread)
# baseline (speedup 1.0000x reference)
.LBB0_344:
	s_or_b64 exec, exec, s[10:11]
	v_add_u32_e32 v168, s49, v209
	v_lshlrev_b32_e32 v168, s47, v168
	s_lshl_b32 s14, s26, 6
	v_add_u32_e32 v128, s48, v168
	v_mov_b64_e32 v[166:167], s[0:1]
	v_mad_i64_i32 v[166:167], s[10:11], v128, s35, v[166:167]
	s_lshl_b32 s14, s14, 1
	v_lshl_add_u64 v[166:167], v[166:167], 0, s[14:15]
	v_lshlrev_b32_e32 v168, 1, v176
	v_mov_b32_e32 v169, 0
	v_lshl_add_u64 v[166:167], v[166:167], 0, v[168:169]
	global_load_dwordx4 v[112:115], v[166:167], off
	global_load_dwordx4 v[116:119], v[166:167], off offset:32
	global_load_dwordx4 v[120:123], v[166:167], off offset:64
	global_load_dwordx4 v[124:127], v[166:167], off offset:96
	s_waitcnt vmcnt(5)
	v_add_u32_e32 v0, v206, v207
	s_waitcnt vmcnt(4)
	ds_write_b128 v0, v[6:9]
	v_add_u32_e32 v6, v206, v208
	ds_write_b128 v6, v[10:13] offset:55296
	ds_write_b128 v0, v[14:17] offset:9216
	ds_write_b128 v196, v[18:21] offset:55296
	ds_write_b128 v0, v[22:25] offset:18432
	ds_write_b128 v202, v[2:5] offset:55296
	ds_write_b128 v0, v[34:37] offset:27648
	ds_write_b128 v203, v[30:33] offset:55296
	ds_write_b128 v0, v[38:41] offset:36864
	ds_write_b128 v204, v[26:29] offset:55296
	ds_write_b128 v0, v[46:49] offset:46080
	ds_write_b128 v238, v[42:45] offset:55296
	v_readlane_b32 s10, v254, 41
	s_cmp_eq_u32 s43, 0
	s_nop 0
	v_mov_b32_e32 v0, s10
	ds_read_b32 v0, v0
	s_mov_b64 s[10:11], exec
	s_and_b64 exec, exec, s[38:39]
	v_mov_b32_e32 v166, 0x20048
	ds_write_b32 v166, v164
	s_mov_b64 exec, s[10:11]
	s_waitcnt lgkmcnt(0)
	s_barrier
	v_xor_b32_e32 v16, 0x80000000, v0
	v_mov_b32_e32 v166, 0x20048
	ds_read_b32 v166, v166
	s_waitcnt lgkmcnt(0)
	v_readfirstlane_b32 s54, v166
	s_min_u32 s54, s54, 0x747
	s_sub_u32 s54, s54, 0x2c8
	s_cmp_ge_u32 s54, 0x180
	s_cselect_b32 s55, 1, 0
	s_cmp_ge_u32 s54, 0x300
	s_cselect_b32 s55, 2, s55
	s_mul_i32 s68, s55, 0x180
	s_sub_u32 s54, s54, s68
	s_lshr_b32 s68, s54, 5
	s_and_b32 s54, s54, 31
	s_lshl_b32 s69, s55, 1
	s_sub_u32 s76, 5, s69
	s_lshr_b32 s77, s54, s76
	s_lshl_b32 s86, 1, s76
	s_sub_u32 s86, s86, 1
	s_and_b32 s54, s54, s86
	s_lshl_b32 s54, s54, 8
	s_movk_i32 s86, 0x3a00
	v_subrev_u32_e32 v168, 0x180, v194
	v_min_u32_e32 v167, v194, v168
	v_add_u32_e32 v167, s54, v167
	v_subrev_u32_e32 v167, 0x80, v167
	v_max_i32_e32 v167, 0, v167
	v_lshlrev_b32_e32 v167, s69, v167
	v_add_u32_e32 v167, s77, v167
	v_mul_lo_u32 v167, v167, s86
	v_lshl_add_u32 v167, s68, 7, v167
	global_load_dword v166, v167, s[0:1] offset:1536
	global_load_dword v168, v167, s[0:1] offset:3072
	v_and_b32_e32 v169, 0xff, v194
	v_add_u32_e32 v169, s54, v169
	v_lshlrev_b32_e32 v169, s69, v169
	v_add_u32_e32 v169, s77, v169
	v_mul_lo_u32 v169, v169, s86
	v_lshl_add_u32 v169, s68, 7, v169
	global_load_dword v169, v169, s[0:1]
	s_cmp_eq_u32 s43, 0
	s_cbranch_scc1 .LBB0_347
	ds_read_b64_tr_b16 v[2:3], v240 offset:55296
	ds_read_b64_tr_b16 v[4:5], v240 offset:56832
	ds_read_b64_tr_b16 v[6:7], v240 offset:58368
	ds_read_b64_tr_b16 v[8:9], v240 offset:59904
	ds_read_b64_tr_b16 v[10:11], v240 offset:55360
	ds_read_b64_tr_b16 v[12:13], v240 offset:56896
	ds_read_b64_tr_b16 v[64:65], v240 offset:58432
	ds_read_b64_tr_b16 v[66:67], v240 offset:59968
	ds_read_b128 v[48:51], v239 offset:96
	ds_read_b128 v[52:55], v239 offset:64
	ds_read_b128 v[56:59], v239
	ds_read_b128 v[60:63], v239 offset:32
	v_mov_b32_e32 v17, v16
	v_mov_b32_e32 v18, v16
	v_mov_b32_e32 v19, v16
	v_mov_b32_e32 v20, v16
	v_mov_b32_e32 v21, v16
	v_mov_b32_e32 v22, v16
	v_mov_b32_e32 v23, v16
	v_mov_b32_e32 v24, v16
	v_mov_b32_e32 v25, v16
	v_mov_b32_e32 v26, v16
	v_mov_b32_e32 v27, v16
	v_mov_b32_e32 v28, v16
	v_mov_b32_e32 v29, v16
	v_mov_b32_e32 v30, v16
	v_mov_b32_e32 v31, v16
	s_waitcnt lgkmcnt(0)
	v_readlane_b32 s10, v254, 50
	v_readlane_b32 s11, v254, 51
	s_waitcnt vmcnt(6)
	v_mfma_f32_32x32x16_bf16 v[32:47], v[56:59], v[112:115], v[16:31]
	s_waitcnt vmcnt(5)
	v_mfma_f32_32x32x16_bf16 v[32:47], v[60:63], v[116:119], v[32:47]
	s_waitcnt vmcnt(4)
	v_mfma_f32_32x32x16_bf16 v[32:47], v[52:55], v[120:123], v[32:47]
	s_waitcnt vmcnt(3)
	v_mfma_f32_32x32x16_bf16 v[32:47], v[48:51], v[124:127], v[32:47]
	s_nop 11
	v_cndmask_b32_e64 v0, v32, v201, s[72:73]
	v_cndmask_b32_e64 v32, v35, v201, s[10:11]
	v_readlane_b32 s10, v254, 52
	v_readlane_b32 s11, v254, 53
	v_cndmask_b32_e64 v14, v33, v201, s[74:75]
	v_cndmask_b32_e64 v15, v34, v201, s[78:79]
	v_cndmask_b32_e64 v33, v36, v201, s[10:11]
	v_readlane_b32 s10, v254, 54
	v_readlane_b32 s11, v254, 55
	v_exp_f32_e32 v0, v0
	v_exp_f32_e32 v14, v14
	v_cndmask_b32_e64 v34, v37, v201, s[10:11]
	v_readlane_b32 s10, v254, 56
	v_readlane_b32 s11, v254, 57
	v_exp_f32_e32 v15, v15
	v_exp_f32_e32 v34, v34
	v_cndmask_b32_e64 v35, v38, v201, s[10:11]
	v_readlane_b32 s10, v254, 58
	v_readlane_b32 s11, v254, 59
	v_exp_f32_e32 v35, v35
	s_nop 0
	v_cndmask_b32_e64 v36, v39, v201, s[10:11]
	v_readlane_b32 s10, v254, 60
	v_readlane_b32 s11, v254, 61
	v_exp_f32_e32 v36, v36
	s_nop 0
	v_cndmask_b32_e64 v37, v40, v201, s[10:11]
	v_readlane_b32 s10, v254, 62
	v_readlane_b32 s11, v254, 63
	v_exp_f32_e32 v37, v37
	s_nop 0
	v_cndmask_b32_e64 v38, v41, v201, s[10:11]
	v_readlane_b32 s10, v255, 0
	v_readlane_b32 s11, v255, 1
	v_exp_f32_e32 v38, v38
	s_nop 0
	v_cndmask_b32_e64 v39, v42, v201, s[10:11]
	v_readlane_b32 s10, v255, 2
	v_readlane_b32 s11, v255, 3
	v_exp_f32_e32 v39, v39
	s_nop 0
	v_cndmask_b32_e64 v40, v43, v201, s[10:11]
	v_readlane_b32 s10, v255, 4
	v_readlane_b32 s11, v255, 5
	v_exp_f32_e32 v40, v40
	s_nop 0
	v_cndmask_b32_e64 v41, v44, v201, s[10:11]
	v_readlane_b32 s10, v255, 6
	v_readlane_b32 s11, v255, 7
	v_exp_f32_e32 v41, v41
	s_nop 0
	v_cndmask_b32_e64 v42, v45, v201, s[10:11]
	v_readlane_b32 s10, v255, 8
	v_readlane_b32 s11, v255, 9
	v_add_f32_e32 v45, 0, v0
	v_add_f32_e32 v45, v14, v45
	v_cndmask_b32_e64 v43, v46, v201, s[10:11]
	v_exp_f32_e32 v46, v32
	v_add_f32_e32 v45, v15, v45
	v_readlane_b32 s10, v255, 10
	v_readlane_b32 s11, v255, 11
	v_add_f32_e32 v32, v46, v45
	v_exp_f32_e32 v45, v33
	v_exp_f32_e32 v42, v42
	v_cndmask_b32_e64 v44, v47, v201, s[10:11]
	v_exp_f32_e32 v43, v43
	v_add_f32_e32 v32, v45, v32
	v_add_f32_e32 v32, v34, v32
	v_add_f32_e32 v32, v35, v32
	v_add_f32_e32 v32, v36, v32
	v_add_f32_e32 v32, v37, v32
	v_add_f32_e32 v32, v38, v32
	v_add_f32_e32 v32, v39, v32
	v_add_f32_e32 v32, v40, v32
	v_exp_f32_e32 v44, v44
	v_add_f32_e32 v32, v41, v32
	v_add_f32_e32 v32, v42, v32
	v_add_f32_e32 v32, v43, v32
	v_add_f32_e32 v129, v44, v32
	v_cvt_pk_bf16_f32 v32, v0, v14
	v_cvt_pk_bf16_f32 v33, v15, v46
	v_cvt_pk_bf16_f32 v34, v45, v34
	v_cvt_pk_bf16_f32 v35, v35, v36
	v_cvt_pk_bf16_f32 v68, v37, v38
	v_cvt_pk_bf16_f32 v69, v39, v40
	v_cvt_pk_bf16_f32 v70, v41, v42
	v_cvt_pk_bf16_f32 v71, v43, v44
	s_nop 0
	v_mfma_f32_32x32x16_bf16 v[48:63], v[2:5], v[32:35], 0
	v_mfma_f32_32x32x16_bf16 v[32:47], v[10:13], v[32:35], 0
	v_mfma_f32_32x32x16_bf16 v[48:63], v[6:9], v[68:71], v[48:63]
	v_mfma_f32_32x32x16_bf16 v[32:47], v[64:67], v[68:71], v[32:47]
	ds_read_b128 v[2:5], v241 offset:96
	ds_read_b128 v[6:9], v241 offset:64
	ds_read_b128 v[10:13], v241
	ds_read_b128 v[130:133], v241 offset:32
	ds_read_b128 v[134:137], v241 offset:4704
	ds_read_b128 v[138:141], v241 offset:4672
	ds_read_b128 v[142:145], v241 offset:4640
	ds_read_b128 v[64:67], v241 offset:4608
	ds_read_b128 v[146:149], v241 offset:9312
	ds_read_b128 v[150:153], v241 offset:9280
	ds_read_b128 v[154:157], v241 offset:9248
	ds_read_b128 v[158:161], v241 offset:9216
	s_waitcnt lgkmcnt(8)
	s_waitcnt lgkmcnt(4)
	s_waitcnt lgkmcnt(0)
	v_mfma_f32_32x32x16_bf16 v[96:111], v[10:13], v[112:115], v[16:31]
	v_mfma_f32_32x32x16_bf16 v[80:95], v[64:67], v[112:115], v[16:31]
	v_mfma_f32_32x32x16_bf16 v[96:111], v[130:133], v[116:119], v[96:111]
	v_mfma_f32_32x32x16_bf16 v[64:79], v[158:161], v[112:115], v[16:31]
	v_mfma_f32_32x32x16_bf16 v[80:95], v[142:145], v[116:119], v[80:95]
	v_mfma_f32_32x32x16_bf16 v[96:111], v[6:9], v[120:123], v[96:111]
	v_mfma_f32_32x32x16_bf16 v[64:79], v[154:157], v[116:119], v[64:79]
	v_mfma_f32_32x32x16_bf16 v[80:95], v[138:141], v[120:123], v[80:95]
	v_mfma_f32_32x32x16_bf16 v[96:111], v[2:5], v[124:127], v[96:111]
	ds_read_b64_tr_b16 v[2:3], v242 offset:55296
	ds_read_b64_tr_b16 v[4:5], v242 offset:56832
	ds_read_b64_tr_b16 v[6:7], v243 offset:55296
	ds_read_b64_tr_b16 v[8:9], v243 offset:56832
	ds_read_b64_tr_b16 v[10:11], v242 offset:55360
	ds_read_b64_tr_b16 v[12:13], v242 offset:56896
	ds_read_b64_tr_b16 v[130:131], v243 offset:55360
	ds_read_b64_tr_b16 v[132:133], v243 offset:56896
	v_mfma_f32_32x32x16_bf16 v[64:79], v[150:153], v[120:123], v[64:79]
	v_mfma_f32_32x32x16_bf16 v[80:95], v[134:137], v[124:127], v[80:95]
	v_mfma_f32_32x32x16_bf16 v[64:79], v[146:149], v[124:127], v[64:79]
	s_nop 0
	v_exp_f32_e32 v0, v96
	v_exp_f32_e32 v134, v97
	v_exp_f32_e32 v136, v98
	v_exp_f32_e32 v138, v99
	v_exp_f32_e32 v140, v100
	v_exp_f32_e32 v142, v101
	v_exp_f32_e32 v144, v102
	v_exp_f32_e32 v146, v103
	v_exp_f32_e32 v148, v104
	v_exp_f32_e32 v150, v105
	v_exp_f32_e32 v152, v106
	v_exp_f32_e32 v154, v107
	v_exp_f32_e32 v156, v108
	v_exp_f32_e32 v158, v109
	v_exp_f32_e32 v160, v110
	v_exp_f32_e32 v162, v111
	v_cvt_pk_bf16_f32 v96, v0, v134
	v_cvt_pk_bf16_f32 v97, v136, v138
	v_cvt_pk_bf16_f32 v98, v140, v142
	v_cvt_pk_bf16_f32 v99, v144, v146
	v_cvt_pk_bf16_f32 v100, v148, v150
	v_cvt_pk_bf16_f32 v101, v152, v154
	v_cvt_pk_bf16_f32 v102, v156, v158
	v_cvt_pk_bf16_f32 v103, v160, v162
	s_waitcnt lgkmcnt(0)
	s_nop 0
	v_mfma_f32_32x32x16_bf16 v[48:63], v[2:5], v[96:99], v[48:63]
	v_mfma_f32_32x32x16_bf16 v[32:47], v[10:13], v[96:99], v[32:47]
	v_mfma_f32_32x32x16_bf16 v[48:63], v[6:9], v[100:103], v[48:63]
	ds_read_b64_tr_b16 v[2:3], v244 offset:55296
	ds_read_b64_tr_b16 v[4:5], v244 offset:56832
	ds_read_b64_tr_b16 v[8:9], v244 offset:56896
	ds_read_b64_tr_b16 v[6:7], v244 offset:55360
	ds_read_b64_tr_b16 v[10:11], v245 offset:55296
	ds_read_b64_tr_b16 v[12:13], v245 offset:56832
	ds_read_b64_tr_b16 v[98:99], v245 offset:56896
	ds_read_b64_tr_b16 v[96:97], v245 offset:55360
	v_mfma_f32_32x32x16_bf16 v[32:47], v[130:133], v[100:103], v[32:47]
	v_exp_f32_e32 v135, v80
	v_exp_f32_e32 v137, v81
	v_exp_f32_e32 v139, v82
	v_exp_f32_e32 v141, v83
	v_exp_f32_e32 v143, v84
	v_exp_f32_e32 v145, v85
	v_exp_f32_e32 v147, v86
	v_exp_f32_e32 v149, v87
	v_exp_f32_e32 v151, v88
	v_exp_f32_e32 v153, v89
	v_exp_f32_e32 v155, v90
	v_exp_f32_e32 v157, v91
	v_exp_f32_e32 v159, v92
	v_exp_f32_e32 v161, v93
	v_exp_f32_e32 v163, v94
	v_exp_f32_e32 v131, v95
	v_cvt_pk_bf16_f32 v80, v135, v137
	v_cvt_pk_bf16_f32 v81, v139, v141
	v_cvt_pk_bf16_f32 v82, v143, v145
	v_cvt_pk_bf16_f32 v83, v147, v149
	v_cvt_pk_bf16_f32 v84, v151, v153
	v_cvt_pk_bf16_f32 v85, v155, v157
	v_cvt_pk_bf16_f32 v86, v159, v161
	v_cvt_pk_bf16_f32 v87, v163, v131
	s_waitcnt lgkmcnt(0)
	s_nop 0
	v_mfma_f32_32x32x16_bf16 v[48:63], v[2:5], v[80:83], v[48:63]
	v_mfma_f32_32x32x16_bf16 v[32:47], v[6:9], v[80:83], v[32:47]
	v_mfma_f32_32x32x16_bf16 v[48:63], v[10:13], v[84:87], v[48:63]
	ds_read_b64_tr_b16 v[2:3], v246 offset:55296
	ds_read_b64_tr_b16 v[4:5], v246 offset:56832
	ds_read_b64_tr_b16 v[8:9], v246 offset:56896
	ds_read_b64_tr_b16 v[6:7], v246 offset:55360
	ds_read_b64_tr_b16 v[10:11], v247 offset:55296
	ds_read_b64_tr_b16 v[12:13], v247 offset:56832
	ds_read_b64_tr_b16 v[82:83], v247 offset:56896
	ds_read_b64_tr_b16 v[80:81], v247 offset:55360
	v_mfma_f32_32x32x16_bf16 v[32:47], v[96:99], v[84:87], v[32:47]
	v_exp_f32_e32 v15, v64
	v_exp_f32_e32 v84, v65
	v_exp_f32_e32 v92, v66
	v_exp_f32_e32 v90, v67
	v_exp_f32_e32 v100, v68
	v_exp_f32_e32 v98, v69
	v_exp_f32_e32 v108, v70
	v_exp_f32_e32 v106, v71
	v_exp_f32_e32 v110, v72
	v_exp_f32_e32 v14, v73
	v_exp_f32_e32 v88, v74
	v_exp_f32_e32 v86, v75
	v_exp_f32_e32 v96, v76
	v_exp_f32_e32 v94, v77
	v_exp_f32_e32 v104, v78
	v_exp_f32_e32 v102, v79
	v_cvt_pk_bf16_f32 v64, v15, v84
	v_cvt_pk_bf16_f32 v65, v92, v90
	v_cvt_pk_bf16_f32 v66, v100, v98
	v_cvt_pk_bf16_f32 v67, v108, v106
	v_cvt_pk_bf16_f32 v68, v110, v14
	v_cvt_pk_bf16_f32 v69, v88, v86
	v_cvt_pk_bf16_f32 v70, v96, v94
	v_cvt_pk_bf16_f32 v71, v104, v102
	s_waitcnt lgkmcnt(0)
	v_add_f32_e32 v0, 0, v0
	v_mfma_f32_32x32x16_bf16 v[48:63], v[2:5], v[64:67], v[48:63]
	v_add_f32_e64 v2, v134, v0
	v_add_f32_e64 v3, v135, v1
	v_add_f32_e32 v130, 0, v129
	v_add_f32_e64 v2, v136, v2
	v_add_f32_e64 v3, v137, v3
	v_readlane_b32 s10, v255, 12
	v_add_f32_e32 v2, v138, v2
	v_add_f32_e32 v3, v139, v3
	v_readlane_b32 s11, v255, 13
	v_add_f32_e32 v2, v140, v2
	v_add_f32_e32 v3, v141, v3
	v_mfma_f32_32x32x16_bf16 v[32:47], v[6:9], v[64:67], v[32:47]
	v_add_f32_e64 v2, v142, v2
	v_add_f32_e64 v3, v143, v3
	v_add_f32_e32 v0, 0, v15
	v_add_f32_e64 v2, v144, v2
	v_add_f32_e64 v3, v145, v3
	v_add_f32_e32 v2, v146, v2
	v_add_f32_e32 v3, v147, v3
	s_nop 0
	v_add_f32_e32 v2, v148, v2
	v_add_f32_e32 v3, v149, v3
	v_mfma_f32_32x32x16_bf16 v[48:63], v[10:13], v[68:71], v[48:63]
	v_add_f32_e64 v2, v150, v2
	v_add_f32_e64 v3, v151, v3
	v_add_f32_e64 v2, v152, v2
	v_add_f32_e64 v3, v153, v3
	v_add_f32_e64 v2, v154, v2
	v_add_f32_e64 v3, v155, v3
	v_add_f32_e32 v2, v156, v2
	v_add_f32_e32 v3, v157, v3
	v_mfma_f32_32x32x16_bf16 v[32:47], v[80:83], v[68:71], v[32:47]
	v_add_f32_e64 v2, v158, v2
	v_add_f32_e64 v3, v159, v3
	v_mov_b64_e32 v[78:79], v[30:31]
	v_add_f32_e64 v2, v160, v2
	v_add_f32_e64 v3, v161, v3
	v_mov_b64_e32 v[76:77], v[28:29]
	v_add_f32_e32 v2, v162, v2
	v_add_f32_e32 v3, v163, v3
	v_mov_b64_e32 v[74:75], v[26:27]
	v_add_f32_e32 v130, v130, v2
	v_add_f32_e32 v131, v131, v3
	ds_read_b64_tr_b16 v[80:81], v249 offset:55296
	ds_read_b64_tr_b16 v[82:83], v249 offset:56832
	ds_read_b64_tr_b16 v[10:11], v250 offset:55296
	ds_read_b64_tr_b16 v[12:13], v250 offset:56832
	ds_read_b64_tr_b16 v[6:7], v249 offset:55360
	ds_read_b64_tr_b16 v[8:9], v249 offset:56896
	ds_read_b64_tr_b16 v[2:3], v250 offset:55360
	ds_read_b64_tr_b16 v[4:5], v250 offset:56896
	ds_read_b128 v[132:135], v248 offset:96
	ds_read_b128 v[136:139], v248 offset:64
	ds_read_b128 v[140:143], v248
	ds_read_b128 v[144:147], v248 offset:32
	v_mov_b64_e32 v[72:73], v[24:25]
	v_mov_b64_e32 v[70:71], v[22:23]
	v_mov_b64_e32 v[68:69], v[20:21]
	v_mov_b64_e32 v[66:67], v[18:19]
	v_mov_b64_e32 v[64:65], v[16:17]
	s_waitcnt lgkmcnt(0)
	s_nop 0
	v_mfma_f32_32x32x16_bf16 v[64:79], v[140:143], v[112:115], v[64:79]
	v_mfma_f32_32x32x16_bf16 v[64:79], v[144:147], v[116:119], v[64:79]
	v_mfma_f32_32x32x16_bf16 v[64:79], v[136:139], v[120:123], v[64:79]
	v_mfma_f32_32x32x16_bf16 v[64:79], v[132:135], v[124:127], v[64:79]
	s_nop 11
	v_cndmask_b32_e64 v15, v64, v201, s[10:11]
	v_readlane_b32 s10, v255, 14
	v_readlane_b32 s11, v255, 15
	v_cndmask_b32_e64 v15, v15, v64, s[44:45]
	v_cndmask_b32_e64 v17, v201, v65, s[44:45]
	v_cndmask_b32_e64 v18, v66, v201, s[10:11]
	v_readlane_b32 s10, v255, 16
	v_readlane_b32 s11, v255, 17
	v_exp_f32_e32 v85, v15
	v_exp_f32_e32 v93, v17
	v_cndmask_b32_e64 v19, v67, v201, s[10:11]
	v_readlane_b32 s10, v255, 18
	v_readlane_b32 s11, v255, 19
	v_exp_f32_e32 v91, v18
	v_exp_f32_e32 v101, v19
	v_cndmask_b32_e64 v20, v68, v201, s[10:11]
	v_readlane_b32 s10, v255, 20
	v_readlane_b32 s11, v255, 21
	v_add_f32_e32 v18, v84, v0
	v_add_f32_e32 v19, v85, v1
	v_exp_f32_e32 v99, v20
	v_cndmask_b32_e64 v21, v69, v201, s[10:11]
	v_readlane_b32 s10, v255, 22
	v_readlane_b32 s11, v255, 23
	v_add_f32_e32 v18, v92, v18
	v_add_f32_e32 v19, v93, v19
	v_exp_f32_e32 v109, v21
	v_cndmask_b32_e64 v22, v70, v201, s[10:11]
	v_cndmask_b32_e64 v23, v71, v201, s[56:57]
	v_add_f32_e32 v18, v90, v18
	v_add_f32_e32 v19, v91, v19
	v_exp_f32_e32 v107, v22
	v_cndmask_b32_e64 v24, v72, v201, s[58:59]
	v_add_f32_e32 v18, v100, v18
	v_add_f32_e32 v19, v101, v19
	v_exp_f32_e32 v111, v23
	v_cndmask_b32_e64 v25, v73, v201, s[60:61]
	v_exp_f32_e32 v15, v24
	v_add_f32_e32 v18, v98, v18
	v_add_f32_e32 v19, v99, v19
	v_cndmask_b32_e64 v26, v74, v201, s[62:63]
	v_exp_f32_e32 v89, v25
	v_add_f32_e32 v18, v108, v18
	v_add_f32_e32 v19, v109, v19
	v_cndmask_b32_e64 v27, v75, v201, s[64:65]
	v_exp_f32_e32 v87, v26
	v_add_f32_e32 v18, v106, v18
	v_add_f32_e32 v19, v107, v19
	v_cndmask_b32_e64 v28, v76, v201, s[66:67]
	v_exp_f32_e32 v97, v27
	v_add_f32_e32 v18, v110, v18
	v_add_f32_e32 v19, v111, v19
	v_cndmask_b32_e64 v29, v77, v201, s[40:41]
	v_exp_f32_e32 v95, v28
	v_add_f32_e32 v18, v14, v18
	v_add_f32_e32 v19, v15, v19
	v_cndmask_b32_e64 v30, v78, v201, s[8:9]
	v_cndmask_b32_e64 v31, v79, v201, s[4:5]
	v_exp_f32_e32 v105, v29
	v_add_f32_e32 v18, v88, v18
	v_add_f32_e32 v19, v89, v19
	v_exp_f32_e32 v103, v30
	v_exp_f32_e32 v0, v31
	v_add_f32_e32 v18, v86, v18
	v_add_f32_e32 v19, v87, v19
	v_pk_add_f32 v[20:21], v[130:131], v[130:131] op_sel:[0,1] op_sel_hi:[1,0]
	v_add_f32_e32 v18, v96, v18
	v_add_f32_e32 v19, v97, v19
	v_mov_b32_e32 v21, v0
	v_add_f32_e32 v18, v94, v18
	v_add_f32_e32 v19, v95, v19
	s_nop 0
	v_add_f32_e32 v18, v104, v18
	v_add_f32_e32 v19, v105, v19
	s_nop 0
	v_add_f32_e32 v18, v102, v18
	v_add_f32_e32 v19, v103, v19
	s_nop 0
	v_add_f32_e32 v18, v20, v18
	v_add_f32_e32 v19, v21, v19
	s_nop 0
	v_add_f32_e32 v84, v18, v19
	v_cvt_pk_bf16_f32 v18, v85, v93
	v_cvt_pk_bf16_f32 v19, v91, v101
	v_cvt_pk_bf16_f32 v20, v99, v109
	v_cvt_pk_bf16_f32 v21, v107, v111
	v_cvt_pk_bf16_f32 v22, v15, v89
	v_cvt_pk_bf16_f32 v23, v87, v97
	v_cvt_pk_bf16_f32 v24, v95, v105
	v_cvt_pk_bf16_f32 v25, v103, v0
	s_nop 0
	v_mfma_f32_32x32x16_bf16 v[48:63], v[80:83], v[18:21], v[48:63]
	v_mfma_f32_32x32x16_bf16 v[32:47], v[6:9], v[18:21], v[32:47]
	v_mfma_f32_32x32x16_bf16 v[48:63], v[10:13], v[22:25], v[48:63]
	v_mfma_f32_32x32x16_bf16 v[32:47], v[2:5], v[22:25], v[32:47]
	s_cbranch_execz .LBB0_348
	s_branch .LBB0_352

.LBB0_350:
	s_cmpk_lt_i32 s47, 0x80
	s_cbranch_scc1 .LBB0_349
	v_add_u32_e32 v4, 0, v86
	v_add_u32_e32 v15, 0, v85
	ds_read_b64_tr_b16 v[80:81], v4 offset:55296
	ds_read_b64_tr_b16 v[82:83], v4 offset:56832
	ds_read_b64_tr_b16 v[10:11], v4 offset:58368
	ds_read_b64_tr_b16 v[12:13], v4 offset:59904
	ds_read_b64_tr_b16 v[6:7], v4 offset:55360
	ds_read_b64_tr_b16 v[8:9], v4 offset:56896
	ds_read_b64_tr_b16 v[2:3], v4 offset:58432
	ds_read_b64_tr_b16 v[4:5], v4 offset:59968
	ds_read_b128 v[88:91], v15 offset:96
	ds_read_b128 v[92:95], v15 offset:64
	ds_read_b128 v[96:99], v15
	ds_read_b128 v[100:103], v15 offset:32
	v_or_b32_e32 v0, 0x80, v183
	v_add_u32_e32 v0, s43, v0
	v_add_u32_e32 v14, s43, v233
	s_waitcnt lgkmcnt(0)
	s_waitcnt vmcnt(6)
	v_mfma_f32_32x32x16_bf16 v[64:79], v[96:99], v[112:115], v[16:31]
	v_cmp_lt_i32_e64 s[10:11], v182, v14
	v_cmp_gt_u32_e32 vcc, v182, v0
	s_or_b64 vcc, s[10:11], vcc
	v_cmp_ge_u32_e64 s[10:11], v182, v0
	s_waitcnt vmcnt(5)
	v_mfma_f32_32x32x16_bf16 v[64:79], v[100:103], v[116:119], v[64:79]
	s_waitcnt vmcnt(4)
	v_mfma_f32_32x32x16_bf16 v[64:79], v[92:95], v[120:123], v[64:79]
	s_waitcnt vmcnt(3)
	v_mfma_f32_32x32x16_bf16 v[64:79], v[88:91], v[124:127], v[64:79]
	s_nop 11
	v_cndmask_b32_e32 v15, v64, v201, vcc
	v_cmp_lt_i32_e32 vcc, v212, v14
	s_or_b64 vcc, s[10:11], vcc
	v_cmp_gt_u32_e64 s[10:11], v213, v0
	v_cndmask_b32_e32 v64, v65, v201, vcc
	v_cmp_lt_i32_e32 vcc, v213, v14
	s_or_b64 vcc, vcc, s[10:11]
	v_cmp_gt_u32_e64 s[10:11], v214, v0
	v_cndmask_b32_e32 v65, v66, v201, vcc
	v_cmp_lt_i32_e32 vcc, v214, v14
	s_or_b64 vcc, vcc, s[10:11]
	v_cmp_gt_u32_e64 s[10:11], v215, v0
	v_cndmask_b32_e32 v66, v67, v201, vcc
	v_cmp_lt_i32_e32 vcc, v215, v14
	s_or_b64 vcc, vcc, s[10:11]
	v_cmp_gt_u32_e64 s[10:11], v216, v0
	v_cndmask_b32_e32 v67, v68, v201, vcc
	v_cmp_lt_i32_e32 vcc, v216, v14
	s_or_b64 vcc, vcc, s[10:11]
	v_cmp_gt_u32_e64 s[10:11], v217, v0
	v_cndmask_b32_e32 v68, v69, v201, vcc
	v_cmp_lt_i32_e32 vcc, v217, v14
	s_or_b64 vcc, vcc, s[10:11]
	v_cmp_gt_u32_e64 s[10:11], v218, v0
	v_cndmask_b32_e32 v69, v70, v201, vcc
	v_cmp_lt_i32_e32 vcc, v218, v14
	s_or_b64 vcc, vcc, s[10:11]
	v_cmp_gt_u32_e64 s[10:11], v219, v0
	v_cndmask_b32_e32 v70, v71, v201, vcc
	v_cmp_lt_i32_e32 vcc, v219, v14
	s_or_b64 vcc, vcc, s[10:11]
	v_cmp_gt_u32_e64 s[10:11], v220, v0
	v_cndmask_b32_e32 v71, v72, v201, vcc
	v_cmp_lt_i32_e32 vcc, v220, v14
	s_or_b64 vcc, vcc, s[10:11]
	v_cmp_gt_u32_e64 s[10:11], v221, v0
	v_cndmask_b32_e32 v72, v73, v201, vcc
	v_cmp_lt_i32_e32 vcc, v221, v14
	s_or_b64 vcc, vcc, s[10:11]
	v_cmp_gt_u32_e64 s[10:11], v222, v0
	v_cndmask_b32_e32 v73, v74, v201, vcc
	v_cmp_lt_i32_e32 vcc, v222, v14
	s_or_b64 vcc, vcc, s[10:11]
	v_cmp_gt_u32_e64 s[10:11], v223, v0
	v_cndmask_b32_e32 v74, v75, v201, vcc
	v_cmp_lt_i32_e32 vcc, v223, v14
	s_or_b64 vcc, vcc, s[10:11]
	v_cmp_gt_u32_e64 s[10:11], v224, v0
	v_cndmask_b32_e32 v75, v76, v201, vcc
	v_cmp_lt_i32_e32 vcc, v224, v14
	s_or_b64 vcc, vcc, s[10:11]
	v_cmp_gt_u32_e64 s[10:11], v225, v0
	v_cndmask_b32_e32 v76, v77, v201, vcc
	v_cmp_lt_i32_e32 vcc, v225, v14
	s_or_b64 vcc, vcc, s[10:11]
	v_exp_f32_e32 v64, v64
	v_cndmask_b32_e32 v77, v78, v201, vcc
	v_cmp_lt_i32_e32 vcc, v226, v14
	v_exp_f32_e32 v14, v15
	v_exp_f32_e32 v65, v65
	v_exp_f32_e32 v66, v66
	v_exp_f32_e32 v67, v67
	v_add_f32_e32 v15, 0, v14
	v_add_f32_e32 v15, v64, v15
	v_exp_f32_e32 v68, v68
	v_add_f32_e32 v15, v65, v15
	v_exp_f32_e32 v69, v69
	v_add_f32_e32 v15, v66, v15
	v_exp_f32_e32 v70, v70
	v_add_f32_e32 v15, v67, v15
	v_exp_f32_e32 v71, v71
	v_cmp_gt_u32_e64 s[10:11], v226, v0
	v_add_f32_e32 v15, v68, v15
	s_or_b64 vcc, vcc, s[10:11]
	v_add_f32_e32 v15, v69, v15
	v_cndmask_b32_e32 v0, v79, v201, vcc
	v_add_f32_e32 v15, v70, v15
	v_add_f32_e32 v15, v71, v15
	v_exp_f32_e32 v72, v72
	v_exp_f32_e32 v73, v73
	v_exp_f32_e32 v74, v74
	v_exp_f32_e32 v75, v75
	v_exp_f32_e32 v76, v76
	v_exp_f32_e32 v77, v77
	v_exp_f32_e32 v0, v0
	v_cvt_pk_bf16_f32 v64, v14, v64
	v_cvt_pk_bf16_f32 v65, v65, v66
	v_cvt_pk_bf16_f32 v66, v67, v68
	v_cvt_pk_bf16_f32 v67, v69, v70
	v_cvt_pk_bf16_f32 v68, v71, v72
	v_cvt_pk_bf16_f32 v69, v73, v74
	v_cvt_pk_bf16_f32 v70, v75, v76
	v_cvt_pk_bf16_f32 v71, v77, v0
	v_add_f32_e32 v15, v72, v15
	v_mfma_f32_32x32x16_bf16 v[48:63], v[80:83], v[64:67], v[48:63]
	v_add_f32_e32 v15, v73, v15
	v_add_f32_e32 v15, v74, v15
	v_add_f32_e32 v15, v75, v15
	v_add_f32_e32 v15, v76, v15
	v_add_f32_e32 v15, v77, v15
	v_add_f32_e32 v15, v0, v15
	v_add_f32_e32 v84, v84, v15
	v_mfma_f32_32x32x16_bf16 v[32:47], v[6:9], v[64:67], v[32:47]
	v_mfma_f32_32x32x16_bf16 v[48:63], v[10:13], v[68:71], v[48:63]
	v_mfma_f32_32x32x16_bf16 v[32:47], v[2:5], v[68:71], v[32:47]
	s_branch .LBB0_349
